# hand-scheduled attention inner loop for NSA-selected items only
# speedup vs baseline: 1.1036x; 1.0121x over previous
; #define TIDX get_tid_()
; template <class KP, class VP, class ACT, class FILL>
; DI void attn_loop(AttnSt& st, const bf16x8 (&qf)[4], int k0, int k1, size_t vstride, KP kp, VP vp, ACT act, FILL fill) {
;   KVT cur, nxt;
;   {
;     KVT t0; load_kv(t0, kp(k0), vp(k0), vstride);
; #pragma unroll
;     for (int i = 0; i < 8; ++i) cur.v[i] = t0.v[i];
; #pragma unroll
;     for (int i = 0; i < 4; ++i) cur.k[i] = t0.k[i];
;   }
;   f32x16 s_cur;
;   { const float z = 0.f;
; #pragma unroll
;     for (int i = 0; i < 16; ++i) s_cur[i] = z; }
; #pragma unroll
;   for (int ss = 0; ss < 4; ++ss) s_cur = MFMA32(cur.k[ss], qf[ss], s_cur);
;   {
;     const int kn = (k0 < k1) ? k0 + 1 : k1;
;     const bf16_t* krow = kp(kn);
; #pragma unroll
;     for (int ss = 0; ss < 4; ++ss) nxt.k[ss] = *(const bf16x8*)(krow + 512 * ss);
;   }
; DI void nsa_main_item(const Params& p, int b, int head, int qb, const unsigned char* blut, const float* tbl) {
;   const int lane = TIDX & 63, r = lane & 31, h = lane >> 5;
;   const int g = head / 3, bg = b * 2 + g;
;   const int t = qb * 32 + r;
;   const float* tblh = tbl + head * 32;
;   bf16x8 qf[4];
;   load_q(qf, (const bf16_t*)(p.ws + OFF_QN) + (size_t)(b * 4096 + t) * 384 + head * 64 + 8 * h);
;   const unsigned long long selm = ((const unsigned long long*)(p.ws + OFF_SELM))[(size_t)bg * 4096 + t];
;   const float* gates = (const float*)(p.ws + OFF_GATES) + (size_t)(b * 4096 + t) * 18 + head * 3;
;   const float g1 = gates[1];
;   f32x16 y0, y1;
;   {
;     const bf16_t* oc = (const bf16_t*)(p.ws + OFF_OC) + (size_t)(b * 4096 + t) * 384 + head * 64;
;     const bf16_t* yw = (const bf16_t*)(p.ws + OFF_Y) + (size_t)(b * 4096 + t) * 768 + head * 64;
; #pragma unroll
;     for (int i = 0; i < 16; ++i) { y0[i] = bf2f(oc[crow(i, h)]) + bf2f(yw[crow(i, h)]); y1[i] = bf2f(oc[32 + crow(i, h)]) + bf2f(yw[32 + crow(i, h)]); }
;   }
;   {
;     const bf16_t* K = (const bf16_t*)(p.ws + OFF_KSEL) + (size_t)bg * 4096 * 64;
;     const bf16_t* Vt = (const bf16_t*)(p.ws + OFF_VSELT) + (size_t)bg * 64 * 4096;
;     AttnSt st; attn_init(st);
;     attn_loop(st, qf, 0, qb, 32,
;       [&](int kt) { return K + (size_t)kt * 2048 + (h * 32 + r) * 8; },
;       [&](int kt) { return Vt + (size_t)kt * 2048 + (h * 32 + r) * 4; },
;       [&](int kt) { return __ballot((selm >> (kt >> 1)) & 1ull) != 0ull; },
.LBB0_707:
	s_or_b64 exec, exec, s[8:9]
	v_lshlrev_b32_e32 v1, 2, v188
	v_and_b32_e32 v1, 0x100, v1
	ds_bpermute_b32 v0, v1, v0
	s_movk_i32 s8, 0x1800
	s_waitcnt lgkmcnt(0)
	v_cmp_gt_i32_e32 vcc, s8, v0
	s_mov_b64 s[8:9], -1
	s_and_saveexec_b64 s[14:15], vcc
	s_cbranch_execz .LBB0_702
	s_mov_b32 s8, 0xd5555555
	v_mul_hi_i32 v1, v0, s8
	v_lshrrev_b32_e32 v2, 31, v1
	v_ashrrev_i32_e32 v1, 3, v1
	s_movk_i32 s8, 0x7f
	v_add3_u32 v217, v1, v2, s8
	s_mov_b32 s8, 0x2aaaaaab
	v_mul_hi_i32 v1, v0, s8
	v_lshrrev_b32_e32 v2, 31, v1
	v_lshrrev_b32_e32 v1, 3, v1
	v_add_u32_e32 v1, v1, v2
	v_mul_lo_u32 v1, v1, 48
	v_sub_u32_e32 v0, v0, v1
	v_mul_lo_u16_e32 v1, 43, v0
	v_lshrrev_b16_e32 v2, 15, v1
	v_add_u16_sdwa v1, v1, v2 dst_sel:DWORD dst_unused:UNUSED_PAD src0_sel:BYTE_1 src1_sel:DWORD
	v_bfe_i32 v2, v1, 0, 8
	v_mul_lo_u16_e32 v1, 6, v1
	v_sub_u16_e32 v0, v0, v1
	v_bfe_i32 v28, v0, 0, 8
	v_mov_b32_e32 v0, v129
	v_lshlrev_b32_e32 v31, 5, v217
	v_and_b32_e32 v29, 31, v0
	v_bfe_u32 v30, v0, 5, 1
	v_mul_lo_u16_e32 v0, 0x56, v28
	v_lshrrev_b16_e32 v1, 15, v0
	v_add_u16_sdwa v0, v0, v1 dst_sel:DWORD dst_unused:UNUSED_PAD src0_sel:BYTE_1 src1_sel:DWORD
	v_readlane_b32 s8, v253, 13
	v_bfe_i32 v0, v0, 0, 8
	v_or_b32_e32 v10, v29, v31
	v_readlane_b32 s9, v253, 14
	v_lshl_add_u32 v8, v2, 1, v0
	v_lshl_add_u32 v22, v2, 12, v10
	v_mov_b64_e32 v[0:1], s[8:9]
	s_movk_i32 s23, 0x300
	v_mad_i64_i32 v[0:1], s[8:9], v22, s23, v[0:1]
	v_lshlrev_b32_e32 v2, 6, v28
	v_ashrrev_i32_e32 v3, 31, v2
	v_readlane_b32 s8, v253, 23
	v_lshlrev_b64 v[2:3], 1, v[2:3]
	v_readlane_b32 s9, v253, 24
	v_lshl_add_u64 v[4:5], v[0:1], 0, v[2:3]
	v_lshlrev_b32_e32 v130, 3, v30
	v_mov_b64_e32 v[0:1], s[8:9]
	v_mad_i64_i32 v[0:1], s[8:9], v22, s23, v[0:1]
	v_readlane_b32 s8, v253, 19
	v_readlane_b32 s9, v253, 20
	v_lshl_add_u64 v[0:1], v[0:1], 0, v[2:3]
	v_ashrrev_i32_e32 v9, 31, v8
	v_mov_b64_e32 v[6:7], s[8:9]
	s_movk_i32 s8, 0x600
	v_mad_i64_i32 v[6:7], s[8:9], v22, s8, v[6:7]
	v_lshl_add_u64 v[2:3], v[6:7], 0, v[2:3]
	v_lshl_add_u64 v[12:13], v[0:1], 0, v[130:131]
	v_readlane_b32 s8, v253, 25
	v_lshlrev_b32_e32 v0, 3, v29
	v_lshl_add_u64 v[132:133], v[2:3], 0, v[130:131]
	v_lshlrev_b64 v[14:15], 19, v[8:9]
	v_readlane_b32 s9, v253, 26
	v_lshl_or_b32 v130, v30, 8, v0
	v_lshlrev_b32_e32 v20, 1, v130
	v_lshl_add_u64 v[16:17], s[8:9], 0, v[14:15]
	v_mov_b32_e32 v21, v131
	v_lshl_add_u64 v[148:149], v[16:17], 0, v[20:21]
	global_load_dwordx4 v[0:3], v[148:149], off
	v_lshlrev_b32_e32 v6, 4, v30
	v_mov_b32_e32 v7, v131
	v_lshl_add_u64 v[4:5], v[4:5], 0, v[6:7]
	global_load_dwordx4 v[80:83], v[4:5], off
	v_mov_b64_e32 v[6:7], s[34:35]
	s_movk_i32 s8, 0x48
	v_mad_i64_i32 v[6:7], s[8:9], v22, s8, v[6:7]
	v_mul_i32_i24_e32 v22, 3, v28
	v_ashrrev_i32_e32 v23, 31, v22
	v_cmp_eq_u32_e32 vcc, 0, v217
	v_lshl_add_u64 v[6:7], v[22:23], 2, v[6:7]
	s_mov_b32 s8, 0x165c4000
	v_cndmask_b32_e64 v18, v197, 0, vcc
	v_add_co_u32_e32 v22, vcc, s8, v6
	v_readlane_b32 s8, v253, 21
	s_nop 0
	v_addc_co_u32_e32 v23, vcc, 0, v7, vcc
	global_load_dwordx4 v[84:87], v[4:5], off offset:32
	global_load_dwordx4 v[88:91], v[4:5], off offset:64
	global_load_dwordx4 v[92:95], v[4:5], off offset:96
	global_load_dwordx2 v[136:137], v[12:13], off offset:64
	global_load_dwordx2 v[144:145], v[12:13], off offset:80
	global_load_dwordx2 v[150:151], v[12:13], off offset:32
	global_load_dwordx2 v[160:161], v[12:13], off offset:48
	global_load_dwordx2 v[134:135], v[132:133], off
	global_load_dwordx2 v[142:143], v[132:133], off offset:16
	global_load_dwordx2 v[152:153], v[132:133], off offset:32
	global_load_dwordx2 v[162:163], v[132:133], off offset:48
	global_load_dwordx2 v[154:155], v[12:13], off offset:96
	global_load_dwordx2 v[164:165], v[12:13], off offset:112
	global_load_dwordx4 v[4:7], v[148:149], off offset:1024
	global_load_dwordx2 v[138:139], v[132:133], off offset:64
	global_load_dwordx2 v[146:147], v[132:133], off offset:80
	global_load_dwordx2 v[158:159], v[132:133], off offset:96
	global_load_dwordx2 v[166:167], v[132:133], off offset:112
	v_lshlrev_b64 v[8:9], 15, v[8:9]
	v_readlane_b32 s9, v253, 22
	v_mov_b32_e32 v11, v131
	v_mov_b32_e32 v19, v131
	v_lshl_add_u64 v[8:9], s[8:9], 0, v[8:9]
	v_lshl_add_u64 v[24:25], v[10:11], 3, v[8:9]
	v_lshl_add_u64 v[26:27], v[16:17], 0, v[18:19]
	global_load_dwordx4 v[8:11], v[148:149], off offset:2048
	global_load_dwordx2 v[168:169], v[24:25], off
	global_load_dword v218, v[22:23], off offset:4
	global_load_dwordx2 v[140:141], v[12:13], off
	global_load_dwordx2 v[156:157], v[12:13], off offset:16
	global_load_dwordx4 v[16:19], v[148:149], off offset:3072
	v_readlane_b32 s8, v253, 27
	v_readlane_b32 s9, v253, 28
	v_lshl_add_u64 v[12:13], v[26:27], 0, v[20:21]
	global_load_dwordx4 v[108:111], v[12:13], off offset:3072
	global_load_dwordx4 v[104:107], v[12:13], off offset:2048
	global_load_dwordx4 v[100:103], v[12:13], off offset:1024
	global_load_dwordx4 v[96:99], v[12:13], off
	v_lshl_add_u64 v[14:15], s[8:9], 0, v[14:15]
	v_lshl_add_u64 v[170:171], v[14:15], 0, v[130:131]
	global_load_dwordx2 v[114:115], v[170:171], off offset:3584
	global_load_dwordx2 v[112:113], v[170:171], off offset:3072
	global_load_dwordx2 v[118:119], v[170:171], off offset:2560
	global_load_dwordx2 v[116:117], v[170:171], off offset:2048
	global_load_dwordx2 v[122:123], v[170:171], off offset:1536
	global_load_dwordx2 v[120:121], v[170:171], off offset:1024
	global_load_dwordx2 v[126:127], v[170:171], off offset:512
	global_load_dwordx2 v[124:125], v[170:171], off
	s_mov_b32 s56, 0
	s_mov_b32 s57, s56
	s_mov_b32 s58, s56
	s_mov_b32 s59, s56
	s_mov_b32 s60, s56
	s_mov_b32 s61, s56
	s_mov_b32 s62, s56
	s_mov_b32 s63, s56
	s_mov_b32 s64, s56
	s_mov_b32 s65, s56
	s_mov_b32 s66, s56
	s_mov_b32 s67, s56
	s_mov_b32 s68, s56
	s_mov_b32 s69, s56
	s_waitcnt vmcnt(36)
; #define MFMA32(a, b, c) __builtin_amdgcn_mfma_f32_32x32x16_bf16((a), (b), (c), 0, 0, 0)
; template <class KP, class VP, class ACT, class FILL>
; DI void attn_loop(AttnSt& st, const bf16x8 (&qf)[4], int k0, int k1, size_t vstride, KP kp, VP vp, ACT act, FILL fill) {
;   KVT cur, nxt;
;   {
;     KVT t0; load_kv(t0, kp(k0), vp(k0), vstride);
; #pragma unroll
;     for (int i = 0; i < 8; ++i) cur.v[i] = t0.v[i];
; #pragma unroll
;     for (int i = 0; i < 4; ++i) cur.k[i] = t0.k[i];
;   }
;   f32x16 s_cur;
;   { const float z = 0.f;
; #pragma unroll
;     for (int i = 0; i < 16; ++i) s_cur[i] = z; }
; #pragma unroll
;   for (int ss = 0; ss < 4; ++ss) s_cur = MFMA32(cur.k[ss], qf[ss], s_cur);
;   {
;     const int kn = (k0 < k1) ? k0 + 1 : k1;
;     const bf16_t* krow = kp(kn);
; #pragma unroll
;     for (int ss = 0; ss < 4; ++ss) nxt.k[ss] = *(const bf16x8*)(krow + 512 * ss);
;   }
;   for (int kt = k0; kt <= k1; ++kt) {
;     const int kn = (kt < k1) ? kt + 1 : k1;
;     const int kn2 = (kt + 2 <= k1) ? kt + 2 : k1;
;     {
;       const bf16_t* v0 = vp(kn);
; #pragma unroll
;       for (int j = 0; j < 8; ++j) nxt.v[j] = *(const s16x4*)(v0 + 256 * j);
;     }
;     bf16x8 k2[4];
;     {
;       const bf16_t* krow = kp(kn2);
; #pragma unroll
;       for (int ss = 0; ss < 4; ++ss) k2[ss] = *(const bf16x8*)(krow + 512 * ss);
;     }
;     f32x16 s_next;
; #pragma unroll
;     for (int i = 0; i < 16; ++i) s_next[i] = 0.f;
; #pragma unroll
;     for (int ss = 0; ss < 4; ++ss) s_next = MFMA32(nxt.k[ss], qf[ss], s_next);
;     if (act(kt)) {
;       float lg[16];
;       fill(kt, s_cur, lg);
;       softmax_step_r(st, lg, cur);
;     }
;     s_cur = s_next;
; #pragma unroll
;     for (int i = 0; i < 8; ++i) cur.v[i] = nxt.v[i];
; #pragma unroll
;     for (int ss = 0; ss < 4; ++ss) nxt.k[ss] = k2[ss];
; DI void nsa_main_item(const Params& p, int b, int head, int qb, const unsigned char* blut, const float* tbl) {
;     ...
;       [&](int kt, const f32x16& s, float (&lg)[16]) {
;         const bool bs = (selm >> (kt >> 1)) & 1ull;
;         if (qb * 32 - (kt * 32 + 31) >= 1513) {
	v_mfma_f32_32x32x16_bf16 v[48:63], v[0:3], v[80:83], 0
	s_mov_b32 s70, s56
	s_mov_b32 s71, s56
	v_lshlrev_b32_e32 v20, 2, v30
	v_lshl_add_u32 v219, v28, 7, 0
	v_subrev_u32_e32 v220, 31, v31
	v_sub_u32_e32 v221, v29, v20
	v_mov_b32_e32 v222, 0
	s_waitcnt vmcnt(22)
	v_mfma_f32_32x32x16_bf16 v[48:63], v[4:7], v[84:87], v[48:63]
	v_mov_b32_e32 v223, 0xff800000
	s_waitcnt vmcnt(17)
	v_mfma_f32_32x32x16_bf16 v[48:63], v[8:11], v[88:91], v[48:63]
	v_mov_b64_e32 v[0:1], s[56:57]
	v_mov_b64_e32 v[14:15], s[70:71]
	v_mov_b64_e32 v[2:3], s[58:59]
	v_mov_b64_e32 v[4:5], s[60:61]
	v_mov_b64_e32 v[6:7], s[62:63]
	v_mov_b64_e32 v[8:9], s[64:65]
	v_mov_b64_e32 v[10:11], s[66:67]
	s_waitcnt vmcnt(12)
	v_mfma_f32_32x32x16_bf16 v[48:63], v[16:19], v[92:95], v[48:63]
	v_mov_b64_e32 v[12:13], s[68:69]
	v_mov_b64_e32 v[30:31], v[14:15]
	s_mov_b64 s[58:59], 0
	v_mov_b64_e32 v[28:29], v[12:13]
	v_mov_b64_e32 v[26:27], v[10:11]
	v_mov_b64_e32 v[24:25], v[8:9]
	v_mov_b64_e32 v[22:23], v[6:7]
	v_mov_b64_e32 v[20:21], v[4:5]
	v_mov_b64_e32 v[18:19], v[2:3]
	v_mov_b64_e32 v[16:17], v[0:1]
	s_waitcnt vmcnt(0)
	v_readfirstlane_b32 s60, v217
	ds_read_b32 v240, v219 offset:4220
	s_mov_b32 s56, 0
	s_mov_b32 s23, 0
	s_min_u32 s24, s23, s60
	s_lshl_b32 s26, s24, 12
	s_mov_b32 s27, 0
	v_lshl_add_u64 v[248:249], v[148:149], 0, s[26:27]
	global_load_dwordx4 v[96:99], v[248:249], off
	global_load_dwordx4 v[100:103], v[248:249], off offset:1024
	global_load_dwordx4 v[104:107], v[248:249], off offset:2048
	global_load_dwordx4 v[108:111], v[248:249], off offset:3072
	s_mov_b32 s23, 1
	s_min_u32 s24, s23, s60
	s_lshl_b32 s26, s24, 12
	s_mov_b32 s27, 0
	v_lshl_add_u64 v[248:249], v[148:149], 0, s[26:27]
	global_load_dwordx4 v[112:115], v[248:249], off
	global_load_dwordx4 v[116:119], v[248:249], off offset:1024
	global_load_dwordx4 v[120:123], v[248:249], off offset:2048
	global_load_dwordx4 v[124:127], v[248:249], off offset:3072
	s_mov_b32 s23, 0
	s_min_u32 s24, s23, s60
	s_lshl_b32 s26, s24, 12
	s_mov_b32 s27, 0
	v_lshl_add_u64 v[250:251], v[170:171], 0, s[26:27]
	global_load_dwordx2 v[64:65], v[250:251], off
	global_load_dwordx2 v[66:67], v[250:251], off offset:512
	global_load_dwordx2 v[68:69], v[250:251], off offset:1024
	global_load_dwordx2 v[70:71], v[250:251], off offset:1536
	global_load_dwordx2 v[72:73], v[250:251], off offset:2048
	global_load_dwordx2 v[74:75], v[250:251], off offset:2560
	global_load_dwordx2 v[76:77], v[250:251], off offset:3072
	global_load_dwordx2 v[78:79], v[250:251], off offset:3584
	s_mov_b32 s23, 1
	s_min_u32 s24, s23, s60
	s_lshl_b32 s26, s24, 12
	s_mov_b32 s27, 0
	v_lshl_add_u64 v[250:251], v[170:171], 0, s[26:27]
	global_load_dwordx2 v[172:173], v[250:251], off
	global_load_dwordx2 v[174:175], v[250:251], off offset:512
	global_load_dwordx2 v[176:177], v[250:251], off offset:1024
	global_load_dwordx2 v[178:179], v[250:251], off offset:1536
	global_load_dwordx2 v[180:181], v[250:251], off offset:2048
	global_load_dwordx2 v[182:183], v[250:251], off offset:2560
	global_load_dwordx2 v[184:185], v[250:251], off offset:3072
	global_load_dwordx2 v[186:187], v[250:251], off offset:3584
	s_waitcnt lgkmcnt(0)
.Lasel_loop:
	s_waitcnt vmcnt(16)
	v_mfma_f32_32x32x16_bf16 v[32:47], v[96:99], v[80:83], 0
	v_mfma_f32_32x32x16_bf16 v[48:63], v[112:115], v[80:83], 0
	v_mfma_f32_32x32x16_bf16 v[32:47], v[100:103], v[84:87], v[32:47]
	v_mfma_f32_32x32x16_bf16 v[48:63], v[116:119], v[84:87], v[48:63]
	v_mfma_f32_32x32x16_bf16 v[32:47], v[104:107], v[88:91], v[32:47]
	v_mfma_f32_32x32x16_bf16 v[48:63], v[120:123], v[88:91], v[48:63]
	v_mfma_f32_32x32x16_bf16 v[32:47], v[108:111], v[92:95], v[32:47]
	v_mfma_f32_32x32x16_bf16 v[48:63], v[124:127], v[92:95], v[48:63]
	s_add_u32 s23, s56, 2
	s_min_u32 s24, s23, s60
	s_lshl_b32 s26, s24, 12
	s_mov_b32 s27, 0
	v_lshl_add_u64 v[248:249], v[148:149], 0, s[26:27]
	global_load_dwordx4 v[96:99], v[248:249], off
	global_load_dwordx4 v[100:103], v[248:249], off offset:1024
	global_load_dwordx4 v[104:107], v[248:249], off offset:2048
	global_load_dwordx4 v[108:111], v[248:249], off offset:3072
	s_add_u32 s23, s56, 3
	s_min_u32 s24, s23, s60
	s_lshl_b32 s26, s24, 12
	s_mov_b32 s27, 0
	v_lshl_add_u64 v[248:249], v[148:149], 0, s[26:27]
	global_load_dwordx4 v[112:115], v[248:249], off
	global_load_dwordx4 v[116:119], v[248:249], off offset:1024
	global_load_dwordx4 v[120:123], v[248:249], off offset:2048
	global_load_dwordx4 v[124:127], v[248:249], off offset:3072
	s_sub_i32 s61, s60, s56
	s_lshr_b32 s23, s56, 1
	v_lshrrev_b64 v[248:249], s23, v[168:169]
	v_and_b32_e32 v248, 1, v248
	v_cmp_eq_u32_e64 s[62:63], 1, v248
	s_cmp_ge_i32 s61, 50
	s_cbranch_scc1 .Lasel_far
	s_lshl_b32 s23, s61, 5
	v_add_u32_e32 v241, s23, v221
	v_subrev_u32_e32 v242, 32, v241
	s_cmp_ge_i32 s61, 2
	s_cbranch_scc1 .Lasel_near_nodiag
; #define NEGINF (-__builtin_inff())
; DI int crow(int i, int h) { return (i & 3) + 8 * (i >> 2) + 4 * h; }
; DI void bias16(const unsigned char* blut, const float* tblh, const int (&dist)[16], float (&bv)[16]) {
;   int bk[16];
; #pragma unroll
;   for (int i = 0; i < 16; ++i) { const int d = dist[i] < 0 ? 0 : (dist[i] > 2048 ? 2048 : dist[i]); bk[i] = blut[d]; }
; #pragma unroll
;   for (int i = 0; i < 16; ++i) asm volatile("" : "+v"(bk[i]));
; #pragma unroll
;   for (int i = 0; i < 16; ++i) bv[i] = tblh[bk[i]];
; #pragma unroll
;   for (int i = 0; i < 16; ++i) asm volatile("" : "+v"(bv[i]));
; }
; DI void nsa_main_item(const Params& p, int b, int head, int qb, const unsigned char* blut, const float* tbl) {
;     ...
;           for (int i = 0; i < 16; ++i) dist[i] = t - (kt * 32 + crow(i, h));
;           bias16(blut, tblh, dist, bv);
; #pragma unroll
;           for (int i = 0; i < 16; ++i) lg[i] = (bs && dist[i] >= 0) ? s[i] + bv[i] : NEGINF;
	v_subrev_u32_e32 v224, 0, v241
	v_subrev_u32_e32 v225, 1, v241
	v_subrev_u32_e32 v226, 2, v241
	v_subrev_u32_e32 v227, 3, v241
	v_subrev_u32_e32 v228, 8, v241
	v_subrev_u32_e32 v229, 9, v241
	v_subrev_u32_e32 v230, 10, v241
	v_subrev_u32_e32 v231, 11, v241
	v_subrev_u32_e32 v232, 16, v241
	v_subrev_u32_e32 v233, 17, v241
	v_subrev_u32_e32 v234, 18, v241
	v_subrev_u32_e32 v235, 19, v241
	v_subrev_u32_e32 v236, 24, v241
	v_subrev_u32_e32 v237, 25, v241
	v_subrev_u32_e32 v238, 26, v241
	v_subrev_u32_e32 v239, 27, v241
	v_med3_i32 v224, v224, 0, v198
	v_med3_i32 v225, v225, 0, v198
	v_med3_i32 v226, v226, 0, v198
	v_med3_i32 v227, v227, 0, v198
	v_med3_i32 v228, v228, 0, v198
	v_med3_i32 v229, v229, 0, v198
	v_med3_i32 v230, v230, 0, v198
	v_med3_i32 v231, v231, 0, v198
	v_med3_i32 v232, v232, 0, v198
	v_med3_i32 v233, v233, 0, v198
	v_med3_i32 v234, v234, 0, v198
	v_med3_i32 v235, v235, 0, v198
	v_med3_i32 v236, v236, 0, v198
	v_med3_i32 v237, v237, 0, v198
	v_med3_i32 v238, v238, 0, v198
	v_med3_i32 v239, v239, 0, v198
	ds_read_u8 v224, v224
	ds_read_u8 v225, v225
	ds_read_u8 v226, v226
	ds_read_u8 v227, v227
	ds_read_u8 v228, v228
	ds_read_u8 v229, v229
	ds_read_u8 v230, v230
	ds_read_u8 v231, v231
	ds_read_u8 v232, v232
	ds_read_u8 v233, v233
	ds_read_u8 v234, v234
	ds_read_u8 v235, v235
	ds_read_u8 v236, v236
	ds_read_u8 v237, v237
	ds_read_u8 v238, v238
	ds_read_u8 v239, v239
	s_waitcnt lgkmcnt(15)
	v_lshl_add_u32 v224, v224, 2, v219
	s_waitcnt lgkmcnt(14)
	v_lshl_add_u32 v225, v225, 2, v219
	s_waitcnt lgkmcnt(13)
	v_lshl_add_u32 v226, v226, 2, v219
	s_waitcnt lgkmcnt(12)
	v_lshl_add_u32 v227, v227, 2, v219
	s_waitcnt lgkmcnt(11)
	v_lshl_add_u32 v228, v228, 2, v219
	s_waitcnt lgkmcnt(10)
	v_lshl_add_u32 v229, v229, 2, v219
	s_waitcnt lgkmcnt(9)
	v_lshl_add_u32 v230, v230, 2, v219
	s_waitcnt lgkmcnt(8)
	v_lshl_add_u32 v231, v231, 2, v219
	s_waitcnt lgkmcnt(7)
	v_lshl_add_u32 v232, v232, 2, v219
	s_waitcnt lgkmcnt(6)
	v_lshl_add_u32 v233, v233, 2, v219
	s_waitcnt lgkmcnt(5)
	v_lshl_add_u32 v234, v234, 2, v219
	s_waitcnt lgkmcnt(4)
	v_lshl_add_u32 v235, v235, 2, v219
	s_waitcnt lgkmcnt(3)
	v_lshl_add_u32 v236, v236, 2, v219
	s_waitcnt lgkmcnt(2)
	v_lshl_add_u32 v237, v237, 2, v219
	s_waitcnt lgkmcnt(1)
	v_lshl_add_u32 v238, v238, 2, v219
	s_waitcnt lgkmcnt(0)
	v_lshl_add_u32 v239, v239, 2, v219
	ds_read_b32 v224, v224 offset:4096
	ds_read_b32 v225, v225 offset:4096
	ds_read_b32 v226, v226 offset:4096
	ds_read_b32 v227, v227 offset:4096
	ds_read_b32 v228, v228 offset:4096
	ds_read_b32 v229, v229 offset:4096
	ds_read_b32 v230, v230 offset:4096
	ds_read_b32 v231, v231 offset:4096
	ds_read_b32 v232, v232 offset:4096
	ds_read_b32 v233, v233 offset:4096
	ds_read_b32 v234, v234 offset:4096
	ds_read_b32 v235, v235 offset:4096
	ds_read_b32 v236, v236 offset:4096
	ds_read_b32 v237, v237 offset:4096
	ds_read_b32 v238, v238 offset:4096
	ds_read_b32 v239, v239 offset:4096
	s_waitcnt lgkmcnt(15)
	v_add_f32_e32 v32, v32, v224
	v_cmp_le_i32_e32 vcc, 0, v241
	s_and_b64 vcc, vcc, s[62:63]
	v_cndmask_b32_e32 v32, v199, v32, vcc
	s_waitcnt lgkmcnt(14)
	v_add_f32_e32 v33, v33, v225
	v_cmp_le_i32_e32 vcc, 1, v241
	s_and_b64 vcc, vcc, s[62:63]
	v_cndmask_b32_e32 v33, v199, v33, vcc
	s_waitcnt lgkmcnt(13)
	v_add_f32_e32 v34, v34, v226
	v_cmp_le_i32_e32 vcc, 2, v241
	s_and_b64 vcc, vcc, s[62:63]
	v_cndmask_b32_e32 v34, v199, v34, vcc
	s_waitcnt lgkmcnt(12)
	v_add_f32_e32 v35, v35, v227
	v_cmp_le_i32_e32 vcc, 3, v241
	s_and_b64 vcc, vcc, s[62:63]
	v_cndmask_b32_e32 v35, v199, v35, vcc
	s_waitcnt lgkmcnt(11)
	v_add_f32_e32 v36, v36, v228
	v_cmp_le_i32_e32 vcc, 8, v241
	s_and_b64 vcc, vcc, s[62:63]
	v_cndmask_b32_e32 v36, v199, v36, vcc
	s_waitcnt lgkmcnt(10)
	v_add_f32_e32 v37, v37, v229
	v_cmp_le_i32_e32 vcc, 9, v241
	s_and_b64 vcc, vcc, s[62:63]
	v_cndmask_b32_e32 v37, v199, v37, vcc
	s_waitcnt lgkmcnt(9)
	v_add_f32_e32 v38, v38, v230
	v_cmp_le_i32_e32 vcc, 10, v241
	s_and_b64 vcc, vcc, s[62:63]
	v_cndmask_b32_e32 v38, v199, v38, vcc
	s_waitcnt lgkmcnt(8)
	v_add_f32_e32 v39, v39, v231
	v_cmp_le_i32_e32 vcc, 11, v241
	s_and_b64 vcc, vcc, s[62:63]
	v_cndmask_b32_e32 v39, v199, v39, vcc
	s_waitcnt lgkmcnt(7)
	v_add_f32_e32 v40, v40, v232
	v_cmp_le_i32_e32 vcc, 16, v241
	s_and_b64 vcc, vcc, s[62:63]
	v_cndmask_b32_e32 v40, v199, v40, vcc
	s_waitcnt lgkmcnt(6)
	v_add_f32_e32 v41, v41, v233
	v_cmp_le_i32_e32 vcc, 17, v241
	s_and_b64 vcc, vcc, s[62:63]
	v_cndmask_b32_e32 v41, v199, v41, vcc
	s_waitcnt lgkmcnt(5)
	v_add_f32_e32 v42, v42, v234
	v_cmp_le_i32_e32 vcc, 18, v241
	s_and_b64 vcc, vcc, s[62:63]
	v_cndmask_b32_e32 v42, v199, v42, vcc
	s_waitcnt lgkmcnt(4)
	v_add_f32_e32 v43, v43, v235
	v_cmp_le_i32_e32 vcc, 19, v241
	s_and_b64 vcc, vcc, s[62:63]
	v_cndmask_b32_e32 v43, v199, v43, vcc
	s_waitcnt lgkmcnt(3)
	v_add_f32_e32 v44, v44, v236
	v_cmp_le_i32_e32 vcc, 24, v241
	s_and_b64 vcc, vcc, s[62:63]
	v_cndmask_b32_e32 v44, v199, v44, vcc
	s_waitcnt lgkmcnt(2)
	v_add_f32_e32 v45, v45, v237
	v_cmp_le_i32_e32 vcc, 25, v241
	s_and_b64 vcc, vcc, s[62:63]
	v_cndmask_b32_e32 v45, v199, v45, vcc
	s_waitcnt lgkmcnt(1)
	v_add_f32_e32 v46, v46, v238
	v_cmp_le_i32_e32 vcc, 26, v241
	s_and_b64 vcc, vcc, s[62:63]
	v_cndmask_b32_e32 v46, v199, v46, vcc
	s_waitcnt lgkmcnt(0)
; #define NEGINF (-__builtin_inff())
; DI int crow(int i, int h) { return (i & 3) + 8 * (i >> 2) + 4 * h; }
; DI void bias16(const unsigned char* blut, const float* tblh, const int (&dist)[16], float (&bv)[16]) {
;   int bk[16];
; #pragma unroll
;   for (int i = 0; i < 16; ++i) { const int d = dist[i] < 0 ? 0 : (dist[i] > 2048 ? 2048 : dist[i]); bk[i] = blut[d]; }
; #pragma unroll
;   for (int i = 0; i < 16; ++i) asm volatile("" : "+v"(bk[i]));
; #pragma unroll
;   for (int i = 0; i < 16; ++i) bv[i] = tblh[bk[i]];
; #pragma unroll
;   for (int i = 0; i < 16; ++i) asm volatile("" : "+v"(bv[i]));
; }
; DI void nsa_main_item(const Params& p, int b, int head, int qb, const unsigned char* blut, const float* tbl) {
;     ...
;           for (int i = 0; i < 16; ++i) dist[i] = t - (kt * 32 + crow(i, h));
;           bias16(blut, tblh, dist, bv);
; #pragma unroll
;           for (int i = 0; i < 16; ++i) lg[i] = (bs && dist[i] >= 0) ? s[i] + bv[i] : NEGINF;
	v_add_f32_e32 v47, v47, v239
	v_cmp_le_i32_e32 vcc, 27, v241
	s_and_b64 vcc, vcc, s[62:63]
	v_cndmask_b32_e32 v47, v199, v47, vcc
	v_subrev_u32_e32 v224, 0, v242
	v_subrev_u32_e32 v225, 1, v242
	v_subrev_u32_e32 v226, 2, v242
	v_subrev_u32_e32 v227, 3, v242
	v_subrev_u32_e32 v228, 8, v242
	v_subrev_u32_e32 v229, 9, v242
	v_subrev_u32_e32 v230, 10, v242
	v_subrev_u32_e32 v231, 11, v242
	v_subrev_u32_e32 v232, 16, v242
	v_subrev_u32_e32 v233, 17, v242
	v_subrev_u32_e32 v234, 18, v242
	v_subrev_u32_e32 v235, 19, v242
	v_subrev_u32_e32 v236, 24, v242
	v_subrev_u32_e32 v237, 25, v242
	v_subrev_u32_e32 v238, 26, v242
	v_subrev_u32_e32 v239, 27, v242
	v_med3_i32 v224, v224, 0, v198
	v_med3_i32 v225, v225, 0, v198
	v_med3_i32 v226, v226, 0, v198
	v_med3_i32 v227, v227, 0, v198
	v_med3_i32 v228, v228, 0, v198
	v_med3_i32 v229, v229, 0, v198
	v_med3_i32 v230, v230, 0, v198
	v_med3_i32 v231, v231, 0, v198
	v_med3_i32 v232, v232, 0, v198
	v_med3_i32 v233, v233, 0, v198
	v_med3_i32 v234, v234, 0, v198
	v_med3_i32 v235, v235, 0, v198
	v_med3_i32 v236, v236, 0, v198
	v_med3_i32 v237, v237, 0, v198
	v_med3_i32 v238, v238, 0, v198
	v_med3_i32 v239, v239, 0, v198
	ds_read_u8 v224, v224
	ds_read_u8 v225, v225
	ds_read_u8 v226, v226
	ds_read_u8 v227, v227
	ds_read_u8 v228, v228
	ds_read_u8 v229, v229
	ds_read_u8 v230, v230
	ds_read_u8 v231, v231
	ds_read_u8 v232, v232
	ds_read_u8 v233, v233
	ds_read_u8 v234, v234
	ds_read_u8 v235, v235
	ds_read_u8 v236, v236
	ds_read_u8 v237, v237
	ds_read_u8 v238, v238
	ds_read_u8 v239, v239
	s_waitcnt lgkmcnt(15)
	v_lshl_add_u32 v224, v224, 2, v219
	s_waitcnt lgkmcnt(14)
	v_lshl_add_u32 v225, v225, 2, v219
	s_waitcnt lgkmcnt(13)
	v_lshl_add_u32 v226, v226, 2, v219
	s_waitcnt lgkmcnt(12)
	v_lshl_add_u32 v227, v227, 2, v219
	s_waitcnt lgkmcnt(11)
	v_lshl_add_u32 v228, v228, 2, v219
	s_waitcnt lgkmcnt(10)
	v_lshl_add_u32 v229, v229, 2, v219
	s_waitcnt lgkmcnt(9)
	v_lshl_add_u32 v230, v230, 2, v219
	s_waitcnt lgkmcnt(8)
	v_lshl_add_u32 v231, v231, 2, v219
	s_waitcnt lgkmcnt(7)
	v_lshl_add_u32 v232, v232, 2, v219
	s_waitcnt lgkmcnt(6)
	v_lshl_add_u32 v233, v233, 2, v219
	s_waitcnt lgkmcnt(5)
	v_lshl_add_u32 v234, v234, 2, v219
	s_waitcnt lgkmcnt(4)
	v_lshl_add_u32 v235, v235, 2, v219
	s_waitcnt lgkmcnt(3)
	v_lshl_add_u32 v236, v236, 2, v219
	s_waitcnt lgkmcnt(2)
	v_lshl_add_u32 v237, v237, 2, v219
	s_waitcnt lgkmcnt(1)
	v_lshl_add_u32 v238, v238, 2, v219
	s_waitcnt lgkmcnt(0)
	v_lshl_add_u32 v239, v239, 2, v219
	ds_read_b32 v224, v224 offset:4096
	ds_read_b32 v225, v225 offset:4096
	ds_read_b32 v226, v226 offset:4096
	ds_read_b32 v227, v227 offset:4096
	ds_read_b32 v228, v228 offset:4096
	ds_read_b32 v229, v229 offset:4096
	ds_read_b32 v230, v230 offset:4096
	ds_read_b32 v231, v231 offset:4096
	ds_read_b32 v232, v232 offset:4096
	ds_read_b32 v233, v233 offset:4096
	ds_read_b32 v234, v234 offset:4096
	ds_read_b32 v235, v235 offset:4096
	ds_read_b32 v236, v236 offset:4096
	ds_read_b32 v237, v237 offset:4096
	ds_read_b32 v238, v238 offset:4096
	ds_read_b32 v239, v239 offset:4096
	s_waitcnt lgkmcnt(15)
	v_add_f32_e32 v48, v48, v224
	v_cmp_le_i32_e32 vcc, 0, v242
	s_and_b64 vcc, vcc, s[62:63]
	v_cndmask_b32_e32 v48, v199, v48, vcc
	s_waitcnt lgkmcnt(14)
	v_add_f32_e32 v49, v49, v225
	v_cmp_le_i32_e32 vcc, 1, v242
	s_and_b64 vcc, vcc, s[62:63]
	v_cndmask_b32_e32 v49, v199, v49, vcc
	s_waitcnt lgkmcnt(13)
	v_add_f32_e32 v50, v50, v226
	v_cmp_le_i32_e32 vcc, 2, v242
	s_and_b64 vcc, vcc, s[62:63]
	v_cndmask_b32_e32 v50, v199, v50, vcc
	s_waitcnt lgkmcnt(12)
	v_add_f32_e32 v51, v51, v227
	v_cmp_le_i32_e32 vcc, 3, v242
	s_and_b64 vcc, vcc, s[62:63]
	v_cndmask_b32_e32 v51, v199, v51, vcc
	s_waitcnt lgkmcnt(11)
	v_add_f32_e32 v52, v52, v228
	v_cmp_le_i32_e32 vcc, 8, v242
	s_and_b64 vcc, vcc, s[62:63]
	v_cndmask_b32_e32 v52, v199, v52, vcc
	s_waitcnt lgkmcnt(10)
	v_add_f32_e32 v53, v53, v229
	v_cmp_le_i32_e32 vcc, 9, v242
	s_and_b64 vcc, vcc, s[62:63]
	v_cndmask_b32_e32 v53, v199, v53, vcc
	s_waitcnt lgkmcnt(9)
	v_add_f32_e32 v54, v54, v230
	v_cmp_le_i32_e32 vcc, 10, v242
	s_and_b64 vcc, vcc, s[62:63]
	v_cndmask_b32_e32 v54, v199, v54, vcc
	s_waitcnt lgkmcnt(8)
	v_add_f32_e32 v55, v55, v231
	v_cmp_le_i32_e32 vcc, 11, v242
	s_and_b64 vcc, vcc, s[62:63]
	v_cndmask_b32_e32 v55, v199, v55, vcc
	s_waitcnt lgkmcnt(7)
	v_add_f32_e32 v56, v56, v232
	v_cmp_le_i32_e32 vcc, 16, v242
	s_and_b64 vcc, vcc, s[62:63]
	v_cndmask_b32_e32 v56, v199, v56, vcc
	s_waitcnt lgkmcnt(6)
	v_add_f32_e32 v57, v57, v233
	v_cmp_le_i32_e32 vcc, 17, v242
	s_and_b64 vcc, vcc, s[62:63]
	v_cndmask_b32_e32 v57, v199, v57, vcc
	s_waitcnt lgkmcnt(5)
	v_add_f32_e32 v58, v58, v234
	v_cmp_le_i32_e32 vcc, 18, v242
	s_and_b64 vcc, vcc, s[62:63]
	v_cndmask_b32_e32 v58, v199, v58, vcc
	s_waitcnt lgkmcnt(4)
	v_add_f32_e32 v59, v59, v235
	v_cmp_le_i32_e32 vcc, 19, v242
	s_and_b64 vcc, vcc, s[62:63]
	v_cndmask_b32_e32 v59, v199, v59, vcc
	s_waitcnt lgkmcnt(3)
	v_add_f32_e32 v60, v60, v236
	v_cmp_le_i32_e32 vcc, 24, v242
	s_and_b64 vcc, vcc, s[62:63]
	v_cndmask_b32_e32 v60, v199, v60, vcc
	s_waitcnt lgkmcnt(2)
	v_add_f32_e32 v61, v61, v237
	v_cmp_le_i32_e32 vcc, 25, v242
	s_and_b64 vcc, vcc, s[62:63]
	v_cndmask_b32_e32 v61, v199, v61, vcc
	s_waitcnt lgkmcnt(1)
	v_add_f32_e32 v62, v62, v238
	v_cmp_le_i32_e32 vcc, 26, v242
	s_and_b64 vcc, vcc, s[62:63]
	v_cndmask_b32_e32 v62, v199, v62, vcc
	s_waitcnt lgkmcnt(0)
	v_add_f32_e32 v63, v63, v239
	v_cmp_le_i32_e32 vcc, 27, v242
	s_and_b64 vcc, vcc, s[62:63]
	v_cndmask_b32_e32 v63, v199, v63, vcc
	s_branch .Lasel_softmax
; #define NEGINF (-__builtin_inff())
; DI int crow(int i, int h) { return (i & 3) + 8 * (i >> 2) + 4 * h; }
; DI void bias16(const unsigned char* blut, const float* tblh, const int (&dist)[16], float (&bv)[16]) {
;   int bk[16];
; #pragma unroll
;   for (int i = 0; i < 16; ++i) { const int d = dist[i] < 0 ? 0 : (dist[i] > 2048 ? 2048 : dist[i]); bk[i] = blut[d]; }
; #pragma unroll
;   for (int i = 0; i < 16; ++i) asm volatile("" : "+v"(bk[i]));
; #pragma unroll
;   for (int i = 0; i < 16; ++i) bv[i] = tblh[bk[i]];
; #pragma unroll
;   for (int i = 0; i < 16; ++i) asm volatile("" : "+v"(bv[i]));
; }
; DI void nsa_main_item(const Params& p, int b, int head, int qb, const unsigned char* blut, const float* tbl) {
;     ...
;           for (int i = 0; i < 16; ++i) dist[i] = t - (kt * 32 + crow(i, h));
;           bias16(blut, tblh, dist, bv);
; #pragma unroll
;           for (int i = 0; i < 16; ++i) lg[i] = (bs && dist[i] >= 0) ? s[i] + bv[i] : NEGINF;
.Lasel_near_nodiag:
	v_subrev_u32_e32 v224, 0, v241
	v_subrev_u32_e32 v225, 1, v241
	v_subrev_u32_e32 v226, 2, v241
	v_subrev_u32_e32 v227, 3, v241
	v_subrev_u32_e32 v228, 8, v241
	v_subrev_u32_e32 v229, 9, v241
	v_subrev_u32_e32 v230, 10, v241
	v_subrev_u32_e32 v231, 11, v241
	v_subrev_u32_e32 v232, 16, v241
	v_subrev_u32_e32 v233, 17, v241
	v_subrev_u32_e32 v234, 18, v241
	v_subrev_u32_e32 v235, 19, v241
	v_subrev_u32_e32 v236, 24, v241
	v_subrev_u32_e32 v237, 25, v241
	v_subrev_u32_e32 v238, 26, v241
	v_subrev_u32_e32 v239, 27, v241
	v_med3_i32 v224, v224, 0, v198
	v_med3_i32 v225, v225, 0, v198
	v_med3_i32 v226, v226, 0, v198
	v_med3_i32 v227, v227, 0, v198
	v_med3_i32 v228, v228, 0, v198
	v_med3_i32 v229, v229, 0, v198
	v_med3_i32 v230, v230, 0, v198
	v_med3_i32 v231, v231, 0, v198
	v_med3_i32 v232, v232, 0, v198
	v_med3_i32 v233, v233, 0, v198
	v_med3_i32 v234, v234, 0, v198
	v_med3_i32 v235, v235, 0, v198
	v_med3_i32 v236, v236, 0, v198
	v_med3_i32 v237, v237, 0, v198
	v_med3_i32 v238, v238, 0, v198
	v_med3_i32 v239, v239, 0, v198
	ds_read_u8 v224, v224
	ds_read_u8 v225, v225
	ds_read_u8 v226, v226
	ds_read_u8 v227, v227
	ds_read_u8 v228, v228
	ds_read_u8 v229, v229
	ds_read_u8 v230, v230
	ds_read_u8 v231, v231
	ds_read_u8 v232, v232
	ds_read_u8 v233, v233
	ds_read_u8 v234, v234
	ds_read_u8 v235, v235
	ds_read_u8 v236, v236
	ds_read_u8 v237, v237
	ds_read_u8 v238, v238
	ds_read_u8 v239, v239
	s_waitcnt lgkmcnt(15)
	v_lshl_add_u32 v224, v224, 2, v219
	s_waitcnt lgkmcnt(14)
	v_lshl_add_u32 v225, v225, 2, v219
	s_waitcnt lgkmcnt(13)
	v_lshl_add_u32 v226, v226, 2, v219
	s_waitcnt lgkmcnt(12)
	v_lshl_add_u32 v227, v227, 2, v219
	s_waitcnt lgkmcnt(11)
	v_lshl_add_u32 v228, v228, 2, v219
	s_waitcnt lgkmcnt(10)
	v_lshl_add_u32 v229, v229, 2, v219
	s_waitcnt lgkmcnt(9)
	v_lshl_add_u32 v230, v230, 2, v219
	s_waitcnt lgkmcnt(8)
	v_lshl_add_u32 v231, v231, 2, v219
	s_waitcnt lgkmcnt(7)
	v_lshl_add_u32 v232, v232, 2, v219
	s_waitcnt lgkmcnt(6)
	v_lshl_add_u32 v233, v233, 2, v219
	s_waitcnt lgkmcnt(5)
	v_lshl_add_u32 v234, v234, 2, v219
	s_waitcnt lgkmcnt(4)
	v_lshl_add_u32 v235, v235, 2, v219
	s_waitcnt lgkmcnt(3)
	v_lshl_add_u32 v236, v236, 2, v219
	s_waitcnt lgkmcnt(2)
	v_lshl_add_u32 v237, v237, 2, v219
	s_waitcnt lgkmcnt(1)
	v_lshl_add_u32 v238, v238, 2, v219
	s_waitcnt lgkmcnt(0)
	v_lshl_add_u32 v239, v239, 2, v219
	ds_read_b32 v224, v224 offset:4096
	ds_read_b32 v225, v225 offset:4096
	ds_read_b32 v226, v226 offset:4096
	ds_read_b32 v227, v227 offset:4096
	ds_read_b32 v228, v228 offset:4096
	ds_read_b32 v229, v229 offset:4096
	ds_read_b32 v230, v230 offset:4096
	ds_read_b32 v231, v231 offset:4096
	ds_read_b32 v232, v232 offset:4096
	ds_read_b32 v233, v233 offset:4096
	ds_read_b32 v234, v234 offset:4096
	ds_read_b32 v235, v235 offset:4096
	ds_read_b32 v236, v236 offset:4096
	ds_read_b32 v237, v237 offset:4096
	ds_read_b32 v238, v238 offset:4096
	ds_read_b32 v239, v239 offset:4096
	s_waitcnt lgkmcnt(15)
	v_add_f32_e32 v32, v32, v224
	v_cndmask_b32_e64 v32, v199, v32, s[62:63]
	s_waitcnt lgkmcnt(14)
	v_add_f32_e32 v33, v33, v225
	v_cndmask_b32_e64 v33, v199, v33, s[62:63]
	s_waitcnt lgkmcnt(13)
	v_add_f32_e32 v34, v34, v226
	v_cndmask_b32_e64 v34, v199, v34, s[62:63]
	s_waitcnt lgkmcnt(12)
	v_add_f32_e32 v35, v35, v227
	v_cndmask_b32_e64 v35, v199, v35, s[62:63]
	s_waitcnt lgkmcnt(11)
	v_add_f32_e32 v36, v36, v228
	v_cndmask_b32_e64 v36, v199, v36, s[62:63]
	s_waitcnt lgkmcnt(10)
	v_add_f32_e32 v37, v37, v229
	v_cndmask_b32_e64 v37, v199, v37, s[62:63]
	s_waitcnt lgkmcnt(9)
	v_add_f32_e32 v38, v38, v230
	v_cndmask_b32_e64 v38, v199, v38, s[62:63]
	s_waitcnt lgkmcnt(8)
	v_add_f32_e32 v39, v39, v231
	v_cndmask_b32_e64 v39, v199, v39, s[62:63]
	s_waitcnt lgkmcnt(7)
	v_add_f32_e32 v40, v40, v232
	v_cndmask_b32_e64 v40, v199, v40, s[62:63]
	s_waitcnt lgkmcnt(6)
	v_add_f32_e32 v41, v41, v233
	v_cndmask_b32_e64 v41, v199, v41, s[62:63]
	s_waitcnt lgkmcnt(5)
	v_add_f32_e32 v42, v42, v234
	v_cndmask_b32_e64 v42, v199, v42, s[62:63]
	s_waitcnt lgkmcnt(4)
	v_add_f32_e32 v43, v43, v235
	v_cndmask_b32_e64 v43, v199, v43, s[62:63]
	s_waitcnt lgkmcnt(3)
	v_add_f32_e32 v44, v44, v236
	v_cndmask_b32_e64 v44, v199, v44, s[62:63]
	s_waitcnt lgkmcnt(2)
	v_add_f32_e32 v45, v45, v237
	v_cndmask_b32_e64 v45, v199, v45, s[62:63]
	s_waitcnt lgkmcnt(1)
	v_add_f32_e32 v46, v46, v238
	v_cndmask_b32_e64 v46, v199, v46, s[62:63]
	s_waitcnt lgkmcnt(0)
	v_add_f32_e32 v47, v47, v239
	v_cndmask_b32_e64 v47, v199, v47, s[62:63]
	v_subrev_u32_e32 v224, 0, v242
	v_subrev_u32_e32 v225, 1, v242
	v_subrev_u32_e32 v226, 2, v242
	v_subrev_u32_e32 v227, 3, v242
	v_subrev_u32_e32 v228, 8, v242
	v_subrev_u32_e32 v229, 9, v242
	v_subrev_u32_e32 v230, 10, v242
	v_subrev_u32_e32 v231, 11, v242
	v_subrev_u32_e32 v232, 16, v242
	v_subrev_u32_e32 v233, 17, v242
	v_subrev_u32_e32 v234, 18, v242
	v_subrev_u32_e32 v235, 19, v242
	v_subrev_u32_e32 v236, 24, v242
	v_subrev_u32_e32 v237, 25, v242
	v_subrev_u32_e32 v238, 26, v242
	v_subrev_u32_e32 v239, 27, v242
	v_med3_i32 v224, v224, 0, v198
	v_med3_i32 v225, v225, 0, v198
	v_med3_i32 v226, v226, 0, v198
	v_med3_i32 v227, v227, 0, v198
	v_med3_i32 v228, v228, 0, v198
	v_med3_i32 v229, v229, 0, v198
	v_med3_i32 v230, v230, 0, v198
	v_med3_i32 v231, v231, 0, v198
	v_med3_i32 v232, v232, 0, v198
	v_med3_i32 v233, v233, 0, v198
	v_med3_i32 v234, v234, 0, v198
	v_med3_i32 v235, v235, 0, v198
	v_med3_i32 v236, v236, 0, v198
	v_med3_i32 v237, v237, 0, v198
	v_med3_i32 v238, v238, 0, v198
	v_med3_i32 v239, v239, 0, v198
	ds_read_u8 v224, v224
	ds_read_u8 v225, v225
	ds_read_u8 v226, v226
	ds_read_u8 v227, v227
	ds_read_u8 v228, v228
	ds_read_u8 v229, v229
	ds_read_u8 v230, v230
	ds_read_u8 v231, v231
	ds_read_u8 v232, v232
	ds_read_u8 v233, v233
	ds_read_u8 v234, v234
	ds_read_u8 v235, v235
	ds_read_u8 v236, v236
	ds_read_u8 v237, v237
	ds_read_u8 v238, v238
	ds_read_u8 v239, v239
	s_waitcnt lgkmcnt(15)
; #define NEGINF (-__builtin_inff())
; DI int crow(int i, int h) { return (i & 3) + 8 * (i >> 2) + 4 * h; }
; DI void nsa_main_item(const Params& p, int b, int head, int qb, const unsigned char* blut, const float* tbl) {
;     ...
;         if (qb * 32 - (kt * 32 + 31) >= 1513) {
;           const float b31 = tblh[31];
; #pragma unroll
;           for (int i = 0; i < 16; ++i) lg[i] = bs ? s[i] + b31 : NEGINF;
;     ...
;           for (int i = 0; i < 16; ++i) dist[i] = t - (kt * 32 + crow(i, h));
;           bias16(blut, tblh, dist, bv);
; #pragma unroll
;           for (int i = 0; i < 16; ++i) lg[i] = (bs && dist[i] >= 0) ? s[i] + bv[i] : NEGINF;
	v_lshl_add_u32 v224, v224, 2, v219
	s_waitcnt lgkmcnt(14)
	v_lshl_add_u32 v225, v225, 2, v219
	s_waitcnt lgkmcnt(13)
	v_lshl_add_u32 v226, v226, 2, v219
	s_waitcnt lgkmcnt(12)
	v_lshl_add_u32 v227, v227, 2, v219
	s_waitcnt lgkmcnt(11)
	v_lshl_add_u32 v228, v228, 2, v219
	s_waitcnt lgkmcnt(10)
	v_lshl_add_u32 v229, v229, 2, v219
	s_waitcnt lgkmcnt(9)
	v_lshl_add_u32 v230, v230, 2, v219
	s_waitcnt lgkmcnt(8)
	v_lshl_add_u32 v231, v231, 2, v219
	s_waitcnt lgkmcnt(7)
	v_lshl_add_u32 v232, v232, 2, v219
	s_waitcnt lgkmcnt(6)
	v_lshl_add_u32 v233, v233, 2, v219
	s_waitcnt lgkmcnt(5)
	v_lshl_add_u32 v234, v234, 2, v219
	s_waitcnt lgkmcnt(4)
	v_lshl_add_u32 v235, v235, 2, v219
	s_waitcnt lgkmcnt(3)
	v_lshl_add_u32 v236, v236, 2, v219
	s_waitcnt lgkmcnt(2)
	v_lshl_add_u32 v237, v237, 2, v219
	s_waitcnt lgkmcnt(1)
	v_lshl_add_u32 v238, v238, 2, v219
	s_waitcnt lgkmcnt(0)
	v_lshl_add_u32 v239, v239, 2, v219
	ds_read_b32 v224, v224 offset:4096
	ds_read_b32 v225, v225 offset:4096
	ds_read_b32 v226, v226 offset:4096
	ds_read_b32 v227, v227 offset:4096
	ds_read_b32 v228, v228 offset:4096
	ds_read_b32 v229, v229 offset:4096
	ds_read_b32 v230, v230 offset:4096
	ds_read_b32 v231, v231 offset:4096
	ds_read_b32 v232, v232 offset:4096
	ds_read_b32 v233, v233 offset:4096
	ds_read_b32 v234, v234 offset:4096
	ds_read_b32 v235, v235 offset:4096
	ds_read_b32 v236, v236 offset:4096
	ds_read_b32 v237, v237 offset:4096
	ds_read_b32 v238, v238 offset:4096
	ds_read_b32 v239, v239 offset:4096
	s_waitcnt lgkmcnt(15)
	v_add_f32_e32 v48, v48, v224
	v_cndmask_b32_e64 v48, v199, v48, s[62:63]
	s_waitcnt lgkmcnt(14)
	v_add_f32_e32 v49, v49, v225
	v_cndmask_b32_e64 v49, v199, v49, s[62:63]
	s_waitcnt lgkmcnt(13)
	v_add_f32_e32 v50, v50, v226
	v_cndmask_b32_e64 v50, v199, v50, s[62:63]
	s_waitcnt lgkmcnt(12)
	v_add_f32_e32 v51, v51, v227
	v_cndmask_b32_e64 v51, v199, v51, s[62:63]
	s_waitcnt lgkmcnt(11)
	v_add_f32_e32 v52, v52, v228
	v_cndmask_b32_e64 v52, v199, v52, s[62:63]
	s_waitcnt lgkmcnt(10)
	v_add_f32_e32 v53, v53, v229
	v_cndmask_b32_e64 v53, v199, v53, s[62:63]
	s_waitcnt lgkmcnt(9)
	v_add_f32_e32 v54, v54, v230
	v_cndmask_b32_e64 v54, v199, v54, s[62:63]
	s_waitcnt lgkmcnt(8)
	v_add_f32_e32 v55, v55, v231
	v_cndmask_b32_e64 v55, v199, v55, s[62:63]
	s_waitcnt lgkmcnt(7)
	v_add_f32_e32 v56, v56, v232
	v_cndmask_b32_e64 v56, v199, v56, s[62:63]
	s_waitcnt lgkmcnt(6)
	v_add_f32_e32 v57, v57, v233
	v_cndmask_b32_e64 v57, v199, v57, s[62:63]
	s_waitcnt lgkmcnt(5)
	v_add_f32_e32 v58, v58, v234
	v_cndmask_b32_e64 v58, v199, v58, s[62:63]
	s_waitcnt lgkmcnt(4)
	v_add_f32_e32 v59, v59, v235
	v_cndmask_b32_e64 v59, v199, v59, s[62:63]
	s_waitcnt lgkmcnt(3)
	v_add_f32_e32 v60, v60, v236
	v_cndmask_b32_e64 v60, v199, v60, s[62:63]
	s_waitcnt lgkmcnt(2)
	v_add_f32_e32 v61, v61, v237
	v_cndmask_b32_e64 v61, v199, v61, s[62:63]
	s_waitcnt lgkmcnt(1)
	v_add_f32_e32 v62, v62, v238
	v_cndmask_b32_e64 v62, v199, v62, s[62:63]
	s_waitcnt lgkmcnt(0)
	v_add_f32_e32 v63, v63, v239
	v_cndmask_b32_e64 v63, v199, v63, s[62:63]
	s_branch .Lasel_softmax
.Lasel_far:
	s_nop 7
	v_add_f32_e32 v32, v32, v240
	v_add_f32_e32 v33, v33, v240
	v_add_f32_e32 v34, v34, v240
	v_add_f32_e32 v35, v35, v240
	v_add_f32_e32 v36, v36, v240
	v_add_f32_e32 v37, v37, v240
	v_add_f32_e32 v38, v38, v240
	v_add_f32_e32 v39, v39, v240
	v_add_f32_e32 v40, v40, v240
	v_add_f32_e32 v41, v41, v240
	v_add_f32_e32 v42, v42, v240
	v_add_f32_e32 v43, v43, v240
	v_add_f32_e32 v44, v44, v240
	v_add_f32_e32 v45, v45, v240
	v_add_f32_e32 v46, v46, v240
	v_add_f32_e32 v47, v47, v240
	v_add_f32_e32 v48, v48, v240
	v_add_f32_e32 v49, v49, v240
	v_add_f32_e32 v50, v50, v240
	v_add_f32_e32 v51, v51, v240
	v_add_f32_e32 v52, v52, v240
	v_add_f32_e32 v53, v53, v240
	v_add_f32_e32 v54, v54, v240
	v_add_f32_e32 v55, v55, v240
	v_add_f32_e32 v56, v56, v240
	v_add_f32_e32 v57, v57, v240
	v_add_f32_e32 v58, v58, v240
	v_add_f32_e32 v59, v59, v240
	v_add_f32_e32 v60, v60, v240
	v_add_f32_e32 v61, v61, v240
	v_add_f32_e32 v62, v62, v240
	v_add_f32_e32 v63, v63, v240
	v_cndmask_b32_e64 v32, v199, v32, s[62:63]
	v_cndmask_b32_e64 v33, v199, v33, s[62:63]
	v_cndmask_b32_e64 v34, v199, v34, s[62:63]
	v_cndmask_b32_e64 v35, v199, v35, s[62:63]
	v_cndmask_b32_e64 v36, v199, v36, s[62:63]
	v_cndmask_b32_e64 v37, v199, v37, s[62:63]
	v_cndmask_b32_e64 v38, v199, v38, s[62:63]
	v_cndmask_b32_e64 v39, v199, v39, s[62:63]
	v_cndmask_b32_e64 v40, v199, v40, s[62:63]
	v_cndmask_b32_e64 v41, v199, v41, s[62:63]
	v_cndmask_b32_e64 v42, v199, v42, s[62:63]
	v_cndmask_b32_e64 v43, v199, v43, s[62:63]
	v_cndmask_b32_e64 v44, v199, v44, s[62:63]
	v_cndmask_b32_e64 v45, v199, v45, s[62:63]
	v_cndmask_b32_e64 v46, v199, v46, s[62:63]
	v_cndmask_b32_e64 v47, v199, v47, s[62:63]
	v_cndmask_b32_e64 v48, v199, v48, s[62:63]
	v_cndmask_b32_e64 v49, v199, v49, s[62:63]
	v_cndmask_b32_e64 v50, v199, v50, s[62:63]
	v_cndmask_b32_e64 v51, v199, v51, s[62:63]
	v_cndmask_b32_e64 v52, v199, v52, s[62:63]
	v_cndmask_b32_e64 v53, v199, v53, s[62:63]
	v_cndmask_b32_e64 v54, v199, v54, s[62:63]
	v_cndmask_b32_e64 v55, v199, v55, s[62:63]
	v_cndmask_b32_e64 v56, v199, v56, s[62:63]
	v_cndmask_b32_e64 v57, v199, v57, s[62:63]
	v_cndmask_b32_e64 v58, v199, v58, s[62:63]
	v_cndmask_b32_e64 v59, v199, v59, s[62:63]
	v_cndmask_b32_e64 v60, v199, v60, s[62:63]
	v_cndmask_b32_e64 v61, v199, v61, s[62:63]
	v_cndmask_b32_e64 v62, v199, v62, s[62:63]
	v_cndmask_b32_e64 v63, v199, v63, s[62:63]
; #define MFMA32(a, b, c) __builtin_amdgcn_mfma_f32_32x32x16_bf16((a), (b), (c), 0, 0, 0)
; #define NEGINF (-__builtin_inff())
; DI float shx32(float v) { const auto r = __builtin_amdgcn_permlane32_swap(__float_as_uint(v), __float_as_uint(v), false, false); return __uint_as_float((threadIdx.x & 32) ? r[0] : r[1]); }
; DI float ex2(float x) { return __builtin_amdgcn_exp2f(x); }
; DI unsigned pack2(float a, float b) { unsigned r; asm("v_cvt_pk_bf16_f32 %0, %1, %2" : "=v"(r) : "v"(a), "v"(b)); return r; }
; DI void softmax_step_r(AttnSt& st, const float (&lg)[16], const KVT& t) {
;   float mx = NEGINF;
; #pragma unroll
;   for (int i = 0; i < 16; ++i) mx = fmaxf(mx, lg[i]);
;   mx = fmaxf(mx, shx32(mx));
;   if (__ballot(mx > NEGINF) == 0ull) return;
;   const float mnew = fmaxf(st.m, mx);
;   const float muse = (mnew == NEGINF) ? 0.f : mnew;
;   const float alpha = ex2(st.m - muse);
;   float pr[16]; float rs = 0.f;
; #pragma unroll
;   for (int i = 0; i < 16; ++i) { pr[i] = ex2(lg[i] - muse); rs += pr[i]; }
;   st.l = st.l * alpha + rs;
;   if (__ballot(mnew != st.m) != 0ull) {
; #pragma unroll
;     for (int i = 0; i < 16; ++i) { st.o0[i] *= alpha; st.o1[i] *= alpha; }
;   }
;   st.m = mnew;
; #pragma unroll
;   for (int s2 = 0; s2 < 2; ++s2) {
;     u32x4 pk; pk.x = pack2(pr[8 * s2], pr[8 * s2 + 1]); pk.y = pack2(pr[8 * s2 + 2], pr[8 * s2 + 3]); pk.z = pack2(pr[8 * s2 + 4], pr[8 * s2 + 5]); pk.w = pack2(pr[8 * s2 + 6], pr[8 * s2 + 7]);
;     const bf16x8 pb = __builtin_bit_cast(bf16x8, pk);
;     const bf16x8 va0 = __builtin_shufflevector(t.v[s2 * 4 + 0], t.v[s2 * 4 + 1], 0, 1, 2, 3, 4, 5, 6, 7);
;     st.o0 = MFMA32(va0, pb, st.o0);
;     const bf16x8 va1 = __builtin_shufflevector(t.v[s2 * 4 + 2], t.v[s2 * 4 + 3], 0, 1, 2, 3, 4, 5, 6, 7);
;     st.o1 = MFMA32(va1, pb, st.o1);
;   }
; }
; template <class KP, class VP, class ACT, class FILL>
; DI void attn_loop(AttnSt& st, const bf16x8 (&qf)[4], int k0, int k1, size_t vstride, KP kp, VP vp, ACT act, FILL fill) {
;     ...
;     {
;       const bf16_t* v0 = vp(kn);
; #pragma unroll
;       for (int j = 0; j < 8; ++j) nxt.v[j] = *(const s16x4*)(v0 + 256 * j);
;     }
.Lasel_softmax:
	v_max3_f32 v224, v32, v33, v34
	v_max3_f32 v225, v40, v41, v42
	v_max3_f32 v226, v48, v49, v50
	v_max3_f32 v227, v56, v57, v58
	v_max3_f32 v224, v224, v35, v36
	v_max3_f32 v225, v225, v43, v44
	v_max3_f32 v226, v226, v51, v52
	v_max3_f32 v227, v227, v59, v60
	v_max3_f32 v224, v224, v37, v38
	v_max3_f32 v225, v225, v45, v46
	v_max3_f32 v226, v226, v53, v54
	v_max3_f32 v227, v227, v61, v62
	v_max_f32_e32 v224, v224, v39
	v_max_f32_e32 v225, v225, v47
	v_max_f32_e32 v226, v226, v55
	v_max_f32_e32 v227, v227, v63
	v_max3_f32 v224, v224, v225, v226
	v_max_f32_e32 v224, v224, v227
	v_mov_b32_e32 v225, v224
	v_mov_b32_e32 v226, v224
	s_nop 1
	v_permlane32_swap_b32_e32 v225, v226
	v_cndmask_b32_e64 v225, v225, v226, s[12:13]
	v_max_f32_e32 v224, v224, v225
	v_max_f32_e32 v225, v223, v224
	v_cmp_neq_f32_e32 vcc, v199, v225
	s_nop 1
	v_cndmask_b32_e32 v226, 0, v225, vcc
	v_sub_f32_e32 v227, v223, v226
	v_exp_f32_e32 v227, v227
	v_mov_b32_e32 v223, v225
	v_sub_f32_e32 v32, v32, v226
	v_sub_f32_e32 v33, v33, v226
	v_sub_f32_e32 v34, v34, v226
	v_sub_f32_e32 v35, v35, v226
	v_sub_f32_e32 v36, v36, v226
	v_sub_f32_e32 v37, v37, v226
	v_sub_f32_e32 v38, v38, v226
	v_sub_f32_e32 v39, v39, v226
	v_sub_f32_e32 v40, v40, v226
	v_sub_f32_e32 v41, v41, v226
	v_sub_f32_e32 v42, v42, v226
	v_sub_f32_e32 v43, v43, v226
	v_sub_f32_e32 v44, v44, v226
	v_sub_f32_e32 v45, v45, v226
	v_sub_f32_e32 v46, v46, v226
	v_sub_f32_e32 v47, v47, v226
	v_sub_f32_e32 v48, v48, v226
	v_sub_f32_e32 v49, v49, v226
	v_sub_f32_e32 v50, v50, v226
	v_sub_f32_e32 v51, v51, v226
	v_sub_f32_e32 v52, v52, v226
	v_sub_f32_e32 v53, v53, v226
	v_sub_f32_e32 v54, v54, v226
	v_sub_f32_e32 v55, v55, v226
	v_sub_f32_e32 v56, v56, v226
	v_sub_f32_e32 v57, v57, v226
	v_sub_f32_e32 v58, v58, v226
	v_sub_f32_e32 v59, v59, v226
	v_sub_f32_e32 v60, v60, v226
	v_sub_f32_e32 v61, v61, v226
	v_sub_f32_e32 v62, v62, v226
	v_sub_f32_e32 v63, v63, v226
	v_exp_f32_e32 v32, v32
	v_exp_f32_e32 v33, v33
	v_exp_f32_e32 v34, v34
	v_exp_f32_e32 v35, v35
	v_exp_f32_e32 v36, v36
	v_exp_f32_e32 v37, v37
	v_exp_f32_e32 v38, v38
	v_exp_f32_e32 v39, v39
	v_exp_f32_e32 v40, v40
	v_exp_f32_e32 v41, v41
	v_exp_f32_e32 v42, v42
	v_exp_f32_e32 v43, v43
	v_exp_f32_e32 v44, v44
	v_exp_f32_e32 v45, v45
	v_exp_f32_e32 v46, v46
	v_exp_f32_e32 v47, v47
	v_exp_f32_e32 v48, v48
	v_exp_f32_e32 v49, v49
	v_exp_f32_e32 v50, v50
	v_exp_f32_e32 v51, v51
	v_exp_f32_e32 v52, v52
	v_exp_f32_e32 v53, v53
	v_exp_f32_e32 v54, v54
	v_exp_f32_e32 v55, v55
	v_exp_f32_e32 v56, v56
	v_exp_f32_e32 v57, v57
	v_exp_f32_e32 v58, v58
	v_exp_f32_e32 v59, v59
	v_exp_f32_e32 v60, v60
	v_exp_f32_e32 v61, v61
	v_exp_f32_e32 v62, v62
	v_exp_f32_e32 v63, v63
	v_add_f32_e32 v228, v32, v33
	v_add_f32_e32 v229, v40, v41
	v_add_f32_e32 v230, v48, v49
	v_add_f32_e32 v231, v56, v57
	v_add_f32_e32 v228, v228, v34
	v_add_f32_e32 v229, v229, v42
	v_add_f32_e32 v230, v230, v50
	v_add_f32_e32 v231, v231, v58
	v_add_f32_e32 v228, v228, v35
	v_add_f32_e32 v229, v229, v43
	v_add_f32_e32 v230, v230, v51
	v_add_f32_e32 v231, v231, v59
	v_add_f32_e32 v228, v228, v36
	v_add_f32_e32 v229, v229, v44
	v_add_f32_e32 v230, v230, v52
	v_add_f32_e32 v231, v231, v60
	v_add_f32_e32 v228, v228, v37
	v_add_f32_e32 v229, v229, v45
	v_add_f32_e32 v230, v230, v53
	v_add_f32_e32 v231, v231, v61
	v_add_f32_e32 v228, v228, v38
	v_add_f32_e32 v229, v229, v46
	v_add_f32_e32 v230, v230, v54
	v_add_f32_e32 v231, v231, v62
	v_add_f32_e32 v228, v228, v39
	v_add_f32_e32 v229, v229, v47
	v_add_f32_e32 v230, v230, v55
	v_add_f32_e32 v231, v231, v63
	v_add_f32_e32 v228, v228, v229
	v_add_f32_e32 v230, v230, v231
	v_add_f32_e32 v228, v228, v230
	v_fma_f32 v222, v222, v227, v228
	v_mul_f32_e32 v0, v227, v0
	v_mul_f32_e32 v1, v227, v1
	v_mul_f32_e32 v2, v227, v2
	v_mul_f32_e32 v3, v227, v3
	v_mul_f32_e32 v4, v227, v4
	v_mul_f32_e32 v5, v227, v5
	v_mul_f32_e32 v6, v227, v6
	v_mul_f32_e32 v7, v227, v7
	v_mul_f32_e32 v8, v227, v8
	v_mul_f32_e32 v9, v227, v9
	v_mul_f32_e32 v10, v227, v10
	v_mul_f32_e32 v11, v227, v11
	v_mul_f32_e32 v12, v227, v12
	v_mul_f32_e32 v13, v227, v13
	v_mul_f32_e32 v14, v227, v14
	v_mul_f32_e32 v15, v227, v15
	v_mul_f32_e32 v16, v227, v16
	v_mul_f32_e32 v17, v227, v17
	v_mul_f32_e32 v18, v227, v18
	v_mul_f32_e32 v19, v227, v19
	v_mul_f32_e32 v20, v227, v20
	v_mul_f32_e32 v21, v227, v21
	v_mul_f32_e32 v22, v227, v22
	v_mul_f32_e32 v23, v227, v23
	v_mul_f32_e32 v24, v227, v24
	v_mul_f32_e32 v25, v227, v25
	v_mul_f32_e32 v26, v227, v26
	v_mul_f32_e32 v27, v227, v27
	v_mul_f32_e32 v28, v227, v28
	v_mul_f32_e32 v29, v227, v29
	v_mul_f32_e32 v30, v227, v30
	v_mul_f32_e32 v31, v227, v31
	v_cvt_pk_bf16_f32 v224, v32, v33
	v_cvt_pk_bf16_f32 v225, v34, v35
	v_cvt_pk_bf16_f32 v226, v36, v37
	v_cvt_pk_bf16_f32 v227, v38, v39
	v_cvt_pk_bf16_f32 v228, v40, v41
	v_cvt_pk_bf16_f32 v229, v42, v43
	v_cvt_pk_bf16_f32 v230, v44, v45
	v_cvt_pk_bf16_f32 v231, v46, v47
	v_cvt_pk_bf16_f32 v232, v48, v49
	v_cvt_pk_bf16_f32 v233, v50, v51
	v_cvt_pk_bf16_f32 v234, v52, v53
	v_cvt_pk_bf16_f32 v235, v54, v55
	v_cvt_pk_bf16_f32 v236, v56, v57
	v_cvt_pk_bf16_f32 v237, v58, v59
	v_cvt_pk_bf16_f32 v238, v60, v61
	v_cvt_pk_bf16_f32 v239, v62, v63
	s_waitcnt vmcnt(8)
	s_nop 1
	v_mfma_f32_32x32x16_bf16 v[0:15], v[64:67], v[224:227], v[0:15]
	v_mfma_f32_32x32x16_bf16 v[16:31], v[68:71], v[224:227], v[16:31]
	v_mfma_f32_32x32x16_bf16 v[0:15], v[72:75], v[228:231], v[0:15]
	v_mfma_f32_32x32x16_bf16 v[16:31], v[76:79], v[228:231], v[16:31]
	v_mfma_f32_32x32x16_bf16 v[0:15], v[172:175], v[232:235], v[0:15]
	v_mfma_f32_32x32x16_bf16 v[16:31], v[176:179], v[232:235], v[16:31]
	v_mfma_f32_32x32x16_bf16 v[0:15], v[180:183], v[236:239], v[0:15]
	v_mfma_f32_32x32x16_bf16 v[16:31], v[184:187], v[236:239], v[16:31]
	s_add_u32 s23, s56, 2
	s_min_u32 s24, s23, s60
	s_lshl_b32 s26, s24, 12
	s_mov_b32 s27, 0
	v_lshl_add_u64 v[250:251], v[170:171], 0, s[26:27]
	global_load_dwordx2 v[64:65], v[250:251], off
	global_load_dwordx2 v[66:67], v[250:251], off offset:512
	global_load_dwordx2 v[68:69], v[250:251], off offset:1024
	global_load_dwordx2 v[70:71], v[250:251], off offset:1536
	global_load_dwordx2 v[72:73], v[250:251], off offset:2048
	global_load_dwordx2 v[74:75], v[250:251], off offset:2560
	global_load_dwordx2 v[76:77], v[250:251], off offset:3072
	global_load_dwordx2 v[78:79], v[250:251], off offset:3584
	s_add_u32 s23, s56, 3
	s_min_u32 s24, s23, s60
	s_lshl_b32 s26, s24, 12
	s_mov_b32 s27, 0
	v_lshl_add_u64 v[250:251], v[170:171], 0, s[26:27]
	global_load_dwordx2 v[172:173], v[250:251], off
	global_load_dwordx2 v[174:175], v[250:251], off offset:512
	global_load_dwordx2 v[176:177], v[250:251], off offset:1024
	global_load_dwordx2 v[178:179], v[250:251], off offset:1536
	global_load_dwordx2 v[180:181], v[250:251], off offset:2048
	global_load_dwordx2 v[182:183], v[250:251], off offset:2560
	global_load_dwordx2 v[184:185], v[250:251], off offset:3072
	global_load_dwordx2 v[186:187], v[250:251], off offset:3584
	s_add_u32 s56, s56, 2
	s_cmp_le_u32 s56, s60
	s_cbranch_scc1 .Lasel_loop
; template <class KP, class VP, class ACT, class FILL>
; DI void attn_loop(AttnSt& st, const bf16x8 (&qf)[4], int k0, int k1, size_t vstride, KP kp, VP vp, ACT act, FILL fill) {
;     ...
;     if (act(kt)) {
;       float lg[16];
;       fill(kt, s_cur, lg);
;       softmax_step_r(st, lg, cur);
;     }
;     s_cur = s_next;
; #pragma unroll
;     for (int i = 0; i < 8; ++i) cur.v[i] = nxt.v[i];
; #pragma unroll
;     for (int ss = 0; ss < 4; ++ss) nxt.k[ss] = k2[ss];
;   }
	s_nop 15
	s_waitcnt vmcnt(0)
	s_mov_b64 s[58:59], 0
	s_branch .LBB0_701
